# attention output epilogue: bf16 rows staged through the per-wave LDS tile, every store writes 8 full 128-byte head rows
# baseline (speedup 1.0000x reference)
.LBB0_95:
	v_div_scale_f32 v35, s[0:1], v34, v34, 1.0
	v_rcp_f32_e32 v36, v35
	v_div_scale_f32 v37, vcc, 1.0, v34, 1.0
	v_mov_b32_e32 v149, v99
	v_fma_f32 v38, -v35, v36, 1.0
	v_fmac_f32_e32 v36, v38, v36
	v_mul_f32_e32 v38, v37, v36
	v_fma_f32 v39, -v35, v38, v37
	v_fmac_f32_e32 v38, v39, v36
	v_fma_f32 v35, -v35, v38, v37
	v_div_fmas_f32 v35, v35, v36, v38
	v_div_fixup_f32 v34, v35, v34, 1.0
	s_waitcnt vmcnt(0) lgkmcnt(0)
	v_pk_mul_f32 v[0:1], v[34:35], v[0:1] op_sel_hi:[0,1]
	v_pk_mul_f32 v[2:3], v[34:35], v[2:3] op_sel_hi:[0,1]
	v_pk_mul_f32 v[4:5], v[34:35], v[4:5] op_sel_hi:[0,1]
	v_pk_mul_f32 v[6:7], v[34:35], v[6:7] op_sel_hi:[0,1]
	v_pk_mul_f32 v[8:9], v[34:35], v[8:9] op_sel_hi:[0,1]
	v_pk_mul_f32 v[10:11], v[34:35], v[10:11] op_sel_hi:[0,1]
	v_pk_mul_f32 v[12:13], v[34:35], v[12:13] op_sel_hi:[0,1]
	v_pk_mul_f32 v[14:15], v[34:35], v[14:15] op_sel_hi:[0,1]
	v_pk_mul_f32 v[16:17], v[34:35], v[16:17] op_sel_hi:[0,1]
	v_pk_mul_f32 v[18:19], v[34:35], v[18:19] op_sel_hi:[0,1]
	v_pk_mul_f32 v[20:21], v[34:35], v[20:21] op_sel_hi:[0,1]
	v_pk_mul_f32 v[22:23], v[34:35], v[22:23] op_sel_hi:[0,1]
	v_pk_mul_f32 v[24:25], v[34:35], v[24:25] op_sel_hi:[0,1]
	v_pk_mul_f32 v[26:27], v[34:35], v[26:27] op_sel_hi:[0,1]
	v_pk_mul_f32 v[28:29], v[34:35], v[28:29] op_sel_hi:[0,1]
	v_pk_mul_f32 v[30:31], v[34:35], v[30:31] op_sel_hi:[0,1]
	v_cvt_pk_bf16_f32 v16, v16, v17
	v_cvt_pk_bf16_f32 v17, v18, v19
	v_cvt_pk_bf16_f32 v18, v20, v21
	v_cvt_pk_bf16_f32 v19, v22, v23
	v_cvt_pk_bf16_f32 v20, v24, v25
	v_cvt_pk_bf16_f32 v21, v26, v27
	v_cvt_pk_bf16_f32 v22, v28, v29
	v_cvt_pk_bf16_f32 v23, v30, v31
	v_cvt_pk_bf16_f32 v0, v0, v1
	v_cvt_pk_bf16_f32 v1, v2, v3
	v_cvt_pk_bf16_f32 v2, v4, v5
	v_cvt_pk_bf16_f32 v3, v6, v7
	v_cvt_pk_bf16_f32 v4, v8, v9
	v_cvt_pk_bf16_f32 v5, v10, v11
	v_cvt_pk_bf16_f32 v6, v12, v13
	v_cvt_pk_bf16_f32 v7, v14, v15
	v_and_b32_e32 v38, 63, v186
	v_lshrrev_b32_e32 v39, 6, v186
	v_lshlrev_b32_e32 v39, 11, v39
	v_add_u32_e32 v39, 0x20100, v39
	v_lshl_add_u32 v35, v38, 4, v39
	v_and_b32_e32 v34, 15, v38
	v_lshl_add_u32 v34, v34, 7, v39
	v_lshrrev_b32_e32 v36, 5, v38
	v_lshl_add_u32 v34, v36, 3, v34
	v_lshrrev_b32_e32 v36, 3, v38
	v_lshlrev_b32_e32 v36, 11, v36
	v_and_b32_e32 v37, 7, v38
	v_lshl_add_u32 v36, v37, 4, v36
	v_add_u32_e32 v37, 0x4000, v36
	s_add_i32 s14, s14, s3
	s_add_i32 s13, s13, s3
	s_mov_b32 s0, 0x0000ffff
	s_mov_b32 s1, 0x0000ffff
	s_mov_b64 exec, s[0:1]
	ds_write_b64 v34, v[16:17] offset:0
	ds_write_b64 v34, v[0:1] offset:64
	ds_write_b64 v34, v[18:19] offset:16
	ds_write_b64 v34, v[2:3] offset:80
	ds_write_b64 v34, v[20:21] offset:32
	ds_write_b64 v34, v[4:5] offset:96
	ds_write_b64 v34, v[22:23] offset:48
	ds_write_b64 v34, v[6:7] offset:112
	s_mov_b64 exec, -1
	v_readlane_b32 s0, v32, 0
	v_readlane_b32 s1, v33, 0
	s_waitcnt lgkmcnt(0)
	ds_read_b128 v[24:27], v35
	ds_read_b128 v[28:31], v35 offset:1024
	s_nop 1
	s_waitcnt lgkmcnt(0)
	global_store_dwordx4 v36, v[24:27], s[0:1]
	global_store_dwordx4 v37, v[28:31], s[0:1]
	s_mov_b32 s0, 0xffff0000
	s_mov_b32 s1, 0xffff0000
	s_mov_b64 exec, s[0:1]
	ds_write_b64 v34, v[16:17] offset:0
	ds_write_b64 v34, v[0:1] offset:64
	ds_write_b64 v34, v[18:19] offset:16
	ds_write_b64 v34, v[2:3] offset:80
	ds_write_b64 v34, v[20:21] offset:32
	ds_write_b64 v34, v[4:5] offset:96
	ds_write_b64 v34, v[22:23] offset:48
	ds_write_b64 v34, v[6:7] offset:112
	s_mov_b64 exec, -1
	v_readlane_b32 s0, v32, 16
	v_readlane_b32 s1, v33, 16
	s_waitcnt lgkmcnt(0)
	ds_read_b128 v[8:11], v35
	ds_read_b128 v[12:15], v35 offset:1024
	s_nop 1
	s_waitcnt lgkmcnt(0)
	global_store_dwordx4 v36, v[8:11], s[0:1]
	global_store_dwordx4 v37, v[12:15], s[0:1]
	s_cmp_ge_i32 s14, s21
	s_cbranch_scc1 .LBB0_599
